# GEMM K loops stage with saddr-form LDS-DMA (SGPR tile bases via SALU, 32-bit lane offsets) instead of 16 64-bit VALU address adds per iteration
# baseline (speedup 1.0000x reference)
; #define PG8_STAGE(bufoff, gbase, voff) do { _Pragma("unroll") for (int _i = 0; _i < 2; ++_i) \
;         __builtin_amdgcn_global_load_lds((const unsigned*)((const char*)(gbase) + (voff)[_i]), (LAS unsigned*)(lds + (bufoff) + ldsw + _i * 8192), 16, 0, 0); } while (0)
; #define PG8_LDA(dst, b, h) do { _Pragma("unroll") for (int m = 0; m < 4; ++m) _Pragma("unroll") for (int k = 0; k < 2; ++k) dst[m][k] = *(const LAS bf16x8*)(lds + PG8_SA(b, h) + aoff + m * 2048 + k * 1024); } while (0)
; #define PG8_LDB(dst, b, h) do { _Pragma("unroll") for (int n = 0; n < 2; ++n) _Pragma("unroll") for (int k = 0; k < 2; ++k) dst[n][k] = *(const LAS bf16x8*)(lds + PG8_SB(b, h) + boff + n * 2048 + k * 1024); } while (0)
; #define PG8_MMA(ai, bj, At, Bt) do { __builtin_amdgcn_s_setprio(1); _Pragma("unroll") for (int m = 0; m < 4; ++m) _Pragma("unroll") for (int n = 0; n < 2; ++n) _Pragma("unroll") for (int k = 0; k < 2; ++k) \
;         acc[ai][bj][m][n] = __builtin_amdgcn_mfma_f32_16x16x32_bf16(Bt[n][k], At[m][k], acc[ai][bj][m][n], 0, 0, 0); __builtin_amdgcn_s_setprio(0); } while (0)
; #define PG8_WAIT_V(n) asm volatile("s_waitcnt vmcnt(" #n ")" ::: "memory")
; #define PG8_WAIT_L(n) asm volatile("s_waitcnt lgkmcnt(" #n ")" ::: "memory")
; #define PG8_BAR __builtin_amdgcn_s_barrier()
; #define PG8_SCHED __builtin_amdgcn_sched_barrier(0)
; template <class Epi, class Sched>
; __device__ __forceinline__ void gemm_phase(LAS unsigned char* lds, const int K, const Sched& S, const Epi& E) {
;     ...
;             const bool last = (t == nt - 2);
;             const char* a1 = cA + (size_t)(t + 1) * kstep;
;             const char* a2 = last ? nA : cA + (size_t)(t + 2) * kstep; const char* b2 = last ? nB : cB + (size_t)(t + 2) * kstep;
;             const char* a3 = a2 + kstep; const char* b3 = b2 + kstep;
;             PG8_LDB(B0, 0, 0); PG8_LDB(B1, 0, 1); PG8_SCHED; PG8_LDA(At, 0, 0); PG8_STAGE(PG8_SA(1, 1), a1 + hstep, voffA);
;             PG8_WAIT_V(8); PG8_WAIT_L(0); PG8_BAR; PG8_MMA(0, 0, At, B0); PG8_MMA(0, 1, At, B1); PG8_BAR; PG8_SCHED;
;             PG8_LDA(At, 0, 1); PG8_STAGE(PG8_SB(0, 0), b2, voffA); PG8_STAGE(PG8_SB(0, 1), b2 + hstep, voffA); PG8_STAGE(PG8_SA(0, 0), a2, voffA);
;             PG8_WAIT_V(8); PG8_WAIT_L(0); PG8_BAR; PG8_MMA(1, 0, At, B0); PG8_MMA(1, 1, At, B1); PG8_BAR; PG8_SCHED;
.LBB0_142:
	s_add_u32 s10, s8, 0xfffc0080
	s_addc_u32 s11, s9, -1
	s_add_i32 s36, 0, 0x10000
	s_cmp_eq_u32 s27, 12
	s_cselect_b32 s35, s29, s11
	s_cselect_b32 s34, s28, s10
	v_add_u32_e32 v0, s36, v199
	s_cselect_b32 s11, s31, s7
	s_cselect_b32 s10, s30, s5
	s_add_u32 s60, s34, 0x80
	s_addc_u32 s61, s35, 0
	s_add_u32 s62, s10, 0x80
	s_addc_u32 s63, s11, 0
	s_add_i32 s38, 0, 0x14000
	ds_read_b128 v[50:53], v0
	ds_read_b128 v[54:57], v0 offset:1024
	ds_read_b128 v[58:61], v0 offset:2048
	ds_read_b128 v[62:65], v0 offset:3072
	v_add_u32_e32 v0, s38, v199
	ds_read_b128 v[66:69], v0
	ds_read_b128 v[74:77], v0 offset:1024
	ds_read_b128 v[90:93], v0 offset:2048
	ds_read_b128 v[94:97], v0 offset:3072
	s_add_i32 m0, s50, 0xc000
	ds_read_b128 v[150:153], v222
	ds_read_b128 v[154:157], v222 offset:1024
	ds_read_b128 v[174:177], v222 offset:2048
	ds_read_b128 v[178:181], v222 offset:3072
	ds_read_b128 v[204:207], v222 offset:4096
	ds_read_b128 v[208:211], v222 offset:5120
	ds_read_b128 v[212:215], v222 offset:6144
	ds_read_b128 v[226:229], v222 offset:7168
	global_load_lds_dwordx4 v200, s[8:9]
	s_add_i32 m0, s50, 0xe000
	s_nop 0
	global_load_lds_dwordx4 v202, s[8:9]
	s_waitcnt vmcnt(8)
	s_waitcnt lgkmcnt(0)
	s_barrier
	s_setprio 1
	s_waitcnt lgkmcnt(0)
	v_mfma_f32_16x16x32_bf16 v[170:173], v[50:53], v[150:153], v[170:173]
	v_mfma_f32_16x16x32_bf16 v[166:169], v[58:61], v[150:153], v[166:169]
	v_mfma_f32_16x16x32_bf16 v[130:133], v[50:53], v[174:177], v[130:133]
	v_mfma_f32_16x16x32_bf16 v[126:129], v[58:61], v[174:177], v[126:129]
	v_mfma_f32_16x16x32_bf16 v[98:101], v[50:53], v[204:207], v[98:101]
	v_mfma_f32_16x16x32_bf16 v[86:89], v[58:61], v[204:207], v[86:89]
	v_mfma_f32_16x16x32_bf16 v[34:37], v[50:53], v[212:215], v[34:37]
	v_mfma_f32_16x16x32_bf16 v[30:33], v[58:61], v[212:215], v[30:33]
	v_mfma_f32_16x16x32_bf16 v[170:173], v[54:57], v[154:157], v[170:173]
	v_mfma_f32_16x16x32_bf16 v[166:169], v[62:65], v[154:157], v[166:169]
	v_mfma_f32_16x16x32_bf16 v[130:133], v[54:57], v[178:181], v[130:133]
	v_mfma_f32_16x16x32_bf16 v[126:129], v[62:65], v[178:181], v[126:129]
	v_mfma_f32_16x16x32_bf16 v[98:101], v[54:57], v[208:211], v[98:101]
	v_mfma_f32_16x16x32_bf16 v[86:89], v[62:65], v[208:211], v[86:89]
	v_mfma_f32_16x16x32_bf16 v[34:37], v[54:57], v[226:229], v[34:37]
	v_mfma_f32_16x16x32_bf16 v[30:33], v[62:65], v[226:229], v[30:33]
	s_setprio 0
	s_setprio 1
	v_mfma_f32_16x16x32_bf16 v[162:165], v[66:69], v[150:153], v[162:165]
	v_mfma_f32_16x16x32_bf16 v[122:125], v[66:69], v[174:177], v[122:125]
	v_mfma_f32_16x16x32_bf16 v[118:121], v[90:93], v[174:177], v[118:121]
	v_mfma_f32_16x16x32_bf16 v[82:85], v[66:69], v[204:207], v[82:85]
	v_mfma_f32_16x16x32_bf16 v[78:81], v[90:93], v[204:207], v[78:81]
	v_mfma_f32_16x16x32_bf16 v[26:29], v[66:69], v[212:215], v[26:29]
	v_mfma_f32_16x16x32_bf16 v[22:25], v[90:93], v[212:215], v[22:25]
	v_mfma_f32_16x16x32_bf16 v[162:165], v[74:77], v[154:157], v[162:165]
	v_mfma_f32_16x16x32_bf16 v[150:153], v[90:93], v[150:153], v[158:161]
	v_mfma_f32_16x16x32_bf16 v[122:125], v[74:77], v[178:181], v[122:125]
	v_mfma_f32_16x16x32_bf16 v[118:121], v[94:97], v[178:181], v[118:121]
	v_mfma_f32_16x16x32_bf16 v[82:85], v[74:77], v[208:211], v[82:85]
	v_mfma_f32_16x16x32_bf16 v[78:81], v[94:97], v[208:211], v[78:81]
	v_mfma_f32_16x16x32_bf16 v[26:29], v[74:77], v[226:229], v[26:29]
	v_mfma_f32_16x16x32_bf16 v[22:25], v[94:97], v[226:229], v[22:25]
	v_mfma_f32_16x16x32_bf16 v[150:153], v[94:97], v[154:157], v[150:153]
	s_setprio 0
	s_barrier
	s_add_i32 s36, s36, s49
	s_mov_b32 m0, s36
	ds_read_b128 v[154:157], v222 offset:16384
	ds_read_b128 v[158:161], v222 offset:17408
	ds_read_b128 v[174:177], v222 offset:18432
	ds_read_b128 v[178:181], v222 offset:19456
	ds_read_b128 v[204:207], v222 offset:20480
	ds_read_b128 v[208:211], v222 offset:21504
	ds_read_b128 v[212:215], v222 offset:22528
	ds_read_b128 v[226:229], v222 offset:23552
	global_load_lds_dwordx4 v14, s[10:11]
	s_add_i32 m0, s36, 0x2000
	s_add_u32 s36, s10, 0x40000
	s_addc_u32 s37, s11, 0
	s_add_i32 s38, s38, s49
	global_load_lds_dwordx4 v182, s[10:11]
	s_mov_b32 m0, s38
	s_nop 0
	global_load_lds_dwordx4 v14, s[36:37]
	s_add_i32 m0, s38, 0x2000
	s_nop 0
	global_load_lds_dwordx4 v182, s[36:37]
	s_mov_b32 m0, s50
	s_nop 0
	global_load_lds_dwordx4 v14, s[34:35]
	s_mov_b32 m0, s51
	s_nop 0
	global_load_lds_dwordx4 v182, s[34:35]
	s_waitcnt vmcnt(8)
	s_waitcnt lgkmcnt(0)
	s_barrier
	s_setprio 1
	s_waitcnt lgkmcnt(0)
	v_mfma_f32_16x16x32_bf16 v[146:149], v[50:53], v[154:157], v[146:149]
	v_mfma_f32_16x16x32_bf16 v[142:145], v[58:61], v[154:157], v[142:145]
	v_mfma_f32_16x16x32_bf16 v[114:117], v[50:53], v[174:177], v[114:117]
	v_mfma_f32_16x16x32_bf16 v[110:113], v[58:61], v[174:177], v[110:113]
	v_mfma_f32_16x16x32_bf16 v[70:73], v[50:53], v[204:207], v[70:73]
	v_mfma_f32_16x16x32_bf16 v[46:49], v[58:61], v[204:207], v[46:49]
	v_mfma_f32_16x16x32_bf16 v[18:21], v[50:53], v[212:215], v[18:21]
	v_mfma_f32_16x16x32_bf16 v[10:13], v[58:61], v[212:215], v[10:13]
	v_mfma_f32_16x16x32_bf16 v[146:149], v[54:57], v[158:161], v[146:149]
	v_mfma_f32_16x16x32_bf16 v[142:145], v[62:65], v[158:161], v[142:145]
	v_mfma_f32_16x16x32_bf16 v[114:117], v[54:57], v[178:181], v[114:117]
	v_mfma_f32_16x16x32_bf16 v[110:113], v[62:65], v[178:181], v[110:113]
	v_mfma_f32_16x16x32_bf16 v[70:73], v[54:57], v[208:211], v[70:73]
	v_mfma_f32_16x16x32_bf16 v[46:49], v[62:65], v[208:211], v[46:49]
	v_mfma_f32_16x16x32_bf16 v[18:21], v[54:57], v[226:229], v[18:21]
	v_mfma_f32_16x16x32_bf16 v[10:13], v[62:65], v[226:229], v[10:13]
	s_setprio 0
	s_setprio 1
	v_mfma_f32_16x16x32_bf16 v[42:45], v[66:69], v[204:207], v[42:45]
	v_mfma_f32_16x16x32_bf16 v[38:41], v[90:93], v[204:207], v[38:41]
	v_mfma_f32_16x16x32_bf16 v[6:9], v[66:69], v[212:215], v[6:9]
	v_mfma_f32_16x16x32_bf16 v[2:5], v[90:93], v[212:215], v[2:5]
	v_mfma_f32_16x16x32_bf16 v[50:53], v[66:69], v[154:157], v[138:141]
	v_mfma_f32_16x16x32_bf16 v[54:57], v[90:93], v[154:157], v[134:137]
	v_mfma_f32_16x16x32_bf16 v[58:61], v[66:69], v[174:177], v[106:109]
	v_mfma_f32_16x16x32_bf16 v[62:65], v[90:93], v[174:177], v[102:105]
	v_mfma_f32_16x16x32_bf16 v[42:45], v[74:77], v[208:211], v[42:45]
	v_mfma_f32_16x16x32_bf16 v[38:41], v[94:97], v[208:211], v[38:41]
	v_mfma_f32_16x16x32_bf16 v[6:9], v[74:77], v[226:229], v[6:9]
	v_mfma_f32_16x16x32_bf16 v[2:5], v[94:97], v[226:229], v[2:5]
	v_mfma_f32_16x16x32_bf16 v[50:53], v[74:77], v[158:161], v[50:53]
	v_mfma_f32_16x16x32_bf16 v[54:57], v[94:97], v[158:161], v[54:57]
	v_mfma_f32_16x16x32_bf16 v[58:61], v[74:77], v[178:181], v[58:61]
	v_mfma_f32_16x16x32_bf16 v[62:65], v[94:97], v[178:181], v[62:65]
	s_setprio 0
	s_barrier
; #define PG8_STAGE(bufoff, gbase, voff) do { _Pragma("unroll") for (int _i = 0; _i < 2; ++_i) \
;         __builtin_amdgcn_global_load_lds((const unsigned*)((const char*)(gbase) + (voff)[_i]), (LAS unsigned*)(lds + (bufoff) + ldsw + _i * 8192), 16, 0, 0); } while (0)
; #define PG8_LDA(dst, b, h) do { _Pragma("unroll") for (int m = 0; m < 4; ++m) _Pragma("unroll") for (int k = 0; k < 2; ++k) dst[m][k] = *(const LAS bf16x8*)(lds + PG8_SA(b, h) + aoff + m * 2048 + k * 1024); } while (0)
; #define PG8_LDB(dst, b, h) do { _Pragma("unroll") for (int n = 0; n < 2; ++n) _Pragma("unroll") for (int k = 0; k < 2; ++k) dst[n][k] = *(const LAS bf16x8*)(lds + PG8_SB(b, h) + boff + n * 2048 + k * 1024); } while (0)
; #define PG8_MMA(ai, bj, At, Bt) do { __builtin_amdgcn_s_setprio(1); _Pragma("unroll") for (int m = 0; m < 4; ++m) _Pragma("unroll") for (int n = 0; n < 2; ++n) _Pragma("unroll") for (int k = 0; k < 2; ++k) \
;         acc[ai][bj][m][n] = __builtin_amdgcn_mfma_f32_16x16x32_bf16(Bt[n][k], At[m][k], acc[ai][bj][m][n], 0, 0, 0); __builtin_amdgcn_s_setprio(0); } while (0)
; #define PG8_WAIT_V(n) asm volatile("s_waitcnt vmcnt(" #n ")" ::: "memory")
; #define PG8_WAIT_L(n) asm volatile("s_waitcnt lgkmcnt(" #n ")" ::: "memory")
; #define PG8_BAR __builtin_amdgcn_s_barrier()
; #define PG8_SCHED __builtin_amdgcn_sched_barrier(0)
; template <class Epi, class Sched>
; __device__ __forceinline__ void gemm_phase(LAS unsigned char* lds, const int K, const Sched& S, const Epi& E) {
;     ...
;             PG8_LDB(B0, 1, 0); PG8_LDB(B1, 1, 1); PG8_SCHED; PG8_LDA(At, 1, 0); PG8_STAGE(PG8_SA(0, 1), a2 + hstep, voffA);
;             PG8_WAIT_V(8); PG8_WAIT_L(0); PG8_BAR; PG8_MMA(0, 0, At, B0); PG8_MMA(0, 1, At, B1); PG8_BAR; PG8_SCHED;
;             PG8_LDA(At, 1, 1); PG8_STAGE(PG8_SB(1, 0), b3, voffA); PG8_STAGE(PG8_SB(1, 1), b3 + hstep, voffA); PG8_STAGE(PG8_SA(1, 0), a3, voffA);
;             PG8_WAIT_V(8); PG8_WAIT_L(0); PG8_BAR; PG8_MMA(1, 0, At, B0); PG8_MMA(1, 1, At, B1); PG8_BAR; PG8_SCHED;
;         }
	s_add_i32 s36, 0, 0x18000
	v_add_u32_e32 v0, s36, v199
	s_add_i32 s37, 0, 0x1c000
	ds_read_b128 v[66:69], v0
	ds_read_b128 v[74:77], v0 offset:1024
	ds_read_b128 v[90:93], v0 offset:2048
	ds_read_b128 v[94:97], v0 offset:3072
	v_add_u32_e32 v0, s37, v199
	ds_read_b128 v[154:157], v0
	ds_read_b128 v[174:177], v0 offset:1024
	ds_read_b128 v[178:181], v0 offset:2048
	ds_read_b128 v[204:207], v0 offset:3072
	s_add_u32 s34, s34, 0x40000
	s_addc_u32 s35, s35, 0
	s_mov_b32 m0, s52
	ds_read_b128 v[102:105], v222 offset:32768
	ds_read_b128 v[106:109], v222 offset:33792
	ds_read_b128 v[134:137], v222 offset:34816
	ds_read_b128 v[138:141], v222 offset:35840
	ds_read_b128 v[208:211], v222 offset:36864
	ds_read_b128 v[212:215], v222 offset:37888
	ds_read_b128 v[226:229], v222 offset:38912
	ds_read_b128 v[230:233], v222 offset:39936
	global_load_lds_dwordx4 v14, s[34:35]
	s_mov_b32 m0, s53
	s_nop 0
	global_load_lds_dwordx4 v182, s[34:35]
	s_waitcnt vmcnt(8)
	s_waitcnt lgkmcnt(0)
	s_barrier
	s_setprio 1
	s_waitcnt lgkmcnt(0)
	v_mfma_f32_16x16x32_bf16 v[158:161], v[66:69], v[102:105], v[170:173]
	v_mfma_f32_16x16x32_bf16 v[170:173], v[74:77], v[106:109], v[158:161]
	v_mfma_f32_16x16x32_bf16 v[158:161], v[90:93], v[102:105], v[166:169]
	v_mfma_f32_16x16x32_bf16 v[130:133], v[66:69], v[134:137], v[130:133]
	v_mfma_f32_16x16x32_bf16 v[126:129], v[90:93], v[134:137], v[126:129]
	v_mfma_f32_16x16x32_bf16 v[98:101], v[66:69], v[208:211], v[98:101]
	v_mfma_f32_16x16x32_bf16 v[86:89], v[90:93], v[208:211], v[86:89]
	v_mfma_f32_16x16x32_bf16 v[34:37], v[66:69], v[226:229], v[34:37]
	v_mfma_f32_16x16x32_bf16 v[30:33], v[90:93], v[226:229], v[30:33]
	v_mfma_f32_16x16x32_bf16 v[166:169], v[94:97], v[106:109], v[158:161]
	v_mfma_f32_16x16x32_bf16 v[130:133], v[74:77], v[138:141], v[130:133]
	v_mfma_f32_16x16x32_bf16 v[126:129], v[94:97], v[138:141], v[126:129]
	v_mfma_f32_16x16x32_bf16 v[98:101], v[74:77], v[212:215], v[98:101]
	v_mfma_f32_16x16x32_bf16 v[86:89], v[94:97], v[212:215], v[86:89]
	v_mfma_f32_16x16x32_bf16 v[34:37], v[74:77], v[230:233], v[34:37]
	v_mfma_f32_16x16x32_bf16 v[30:33], v[94:97], v[230:233], v[30:33]
	s_setprio 0
	s_setprio 1
	v_mfma_f32_16x16x32_bf16 v[158:161], v[154:157], v[102:105], v[162:165]
	v_mfma_f32_16x16x32_bf16 v[102:105], v[178:181], v[102:105], v[150:153]
	v_mfma_f32_16x16x32_bf16 v[162:165], v[174:177], v[106:109], v[158:161]
	v_mfma_f32_16x16x32_bf16 v[158:161], v[204:207], v[106:109], v[102:105]
	v_mfma_f32_16x16x32_bf16 v[102:105], v[154:157], v[134:137], v[122:125]
	v_mfma_f32_16x16x32_bf16 v[122:125], v[174:177], v[138:141], v[102:105]
	v_mfma_f32_16x16x32_bf16 v[102:105], v[178:181], v[134:137], v[118:121]
	v_mfma_f32_16x16x32_bf16 v[82:85], v[154:157], v[208:211], v[82:85]
	v_mfma_f32_16x16x32_bf16 v[78:81], v[178:181], v[208:211], v[78:81]
	v_mfma_f32_16x16x32_bf16 v[26:29], v[154:157], v[226:229], v[26:29]
	v_mfma_f32_16x16x32_bf16 v[22:25], v[178:181], v[226:229], v[22:25]
	v_mfma_f32_16x16x32_bf16 v[118:121], v[204:207], v[138:141], v[102:105]
	v_mfma_f32_16x16x32_bf16 v[82:85], v[174:177], v[212:215], v[82:85]
	v_mfma_f32_16x16x32_bf16 v[78:81], v[204:207], v[212:215], v[78:81]
	v_mfma_f32_16x16x32_bf16 v[26:29], v[174:177], v[230:233], v[26:29]
	v_mfma_f32_16x16x32_bf16 v[22:25], v[204:207], v[230:233], v[22:25]
	s_setprio 0
	s_barrier
	s_add_i32 s34, s36, s49
	s_mov_b32 m0, s34
	ds_read_b128 v[102:105], v222 offset:49152
	ds_read_b128 v[106:109], v222 offset:50176
	ds_read_b128 v[150:153], v222 offset:51200
	ds_read_b128 v[208:211], v222 offset:52224
	ds_read_b128 v[212:215], v222 offset:53248
	ds_read_b128 v[226:229], v222 offset:54272
	ds_read_b128 v[230:233], v222 offset:55296
	ds_read_b128 v[242:245], v222 offset:56320
	global_load_lds_dwordx4 v14, s[62:63]
	s_add_i32 m0, s34, 0x2000
	s_add_u32 s10, s10, 0x40080
	s_addc_u32 s11, s11, 0
	s_add_i32 s34, s37, s49
	global_load_lds_dwordx4 v182, s[62:63]
	s_mov_b32 m0, s34
	s_nop 0
	global_load_lds_dwordx4 v14, s[10:11]
	s_add_i32 m0, s34, 0x2000
	s_nop 0
	global_load_lds_dwordx4 v182, s[10:11]
	s_mov_b32 m0, s56
	s_nop 0
	global_load_lds_dwordx4 v14, s[60:61]
	s_mov_b32 m0, s57
	s_nop 0
	global_load_lds_dwordx4 v182, s[60:61]
	s_waitcnt vmcnt(8)
	s_waitcnt lgkmcnt(0)
	s_barrier
	s_setprio 1
	s_waitcnt lgkmcnt(0)
	v_mfma_f32_16x16x32_bf16 v[134:137], v[66:69], v[102:105], v[146:149]
	v_mfma_f32_16x16x32_bf16 v[146:149], v[74:77], v[106:109], v[134:137]
	v_mfma_f32_16x16x32_bf16 v[134:137], v[90:93], v[102:105], v[142:145]
	v_mfma_f32_16x16x32_bf16 v[114:117], v[66:69], v[150:153], v[114:117]
	v_mfma_f32_16x16x32_bf16 v[110:113], v[90:93], v[150:153], v[110:113]
	v_mfma_f32_16x16x32_bf16 v[70:73], v[66:69], v[212:215], v[70:73]
	v_mfma_f32_16x16x32_bf16 v[46:49], v[90:93], v[212:215], v[46:49]
	v_mfma_f32_16x16x32_bf16 v[18:21], v[66:69], v[230:233], v[18:21]
	v_mfma_f32_16x16x32_bf16 v[10:13], v[90:93], v[230:233], v[10:13]
	v_mfma_f32_16x16x32_bf16 v[142:145], v[94:97], v[106:109], v[134:137]
	v_mfma_f32_16x16x32_bf16 v[114:117], v[74:77], v[208:211], v[114:117]
	v_mfma_f32_16x16x32_bf16 v[110:113], v[94:97], v[208:211], v[110:113]
	v_mfma_f32_16x16x32_bf16 v[70:73], v[74:77], v[226:229], v[70:73]
	v_mfma_f32_16x16x32_bf16 v[46:49], v[94:97], v[226:229], v[46:49]
	v_mfma_f32_16x16x32_bf16 v[18:21], v[74:77], v[242:245], v[18:21]
	v_mfma_f32_16x16x32_bf16 v[10:13], v[94:97], v[242:245], v[10:13]
	s_setprio 0
	s_setprio 1
	v_mfma_f32_16x16x32_bf16 v[50:53], v[154:157], v[102:105], v[50:53]
	v_mfma_f32_16x16x32_bf16 v[138:141], v[174:177], v[106:109], v[50:53]
	v_mfma_f32_16x16x32_bf16 v[50:53], v[178:181], v[102:105], v[54:57]
	v_mfma_f32_16x16x32_bf16 v[134:137], v[204:207], v[106:109], v[50:53]
	v_mfma_f32_16x16x32_bf16 v[50:53], v[154:157], v[150:153], v[58:61]
	v_mfma_f32_16x16x32_bf16 v[106:109], v[174:177], v[208:211], v[50:53]
	v_mfma_f32_16x16x32_bf16 v[50:53], v[178:181], v[150:153], v[62:65]
	v_mfma_f32_16x16x32_bf16 v[42:45], v[154:157], v[212:215], v[42:45]
	v_mfma_f32_16x16x32_bf16 v[38:41], v[178:181], v[212:215], v[38:41]
	v_mfma_f32_16x16x32_bf16 v[6:9], v[154:157], v[230:233], v[6:9]
	v_mfma_f32_16x16x32_bf16 v[2:5], v[178:181], v[230:233], v[2:5]
	v_mfma_f32_16x16x32_bf16 v[102:105], v[204:207], v[208:211], v[50:53]
	v_mfma_f32_16x16x32_bf16 v[42:45], v[174:177], v[226:229], v[42:45]
	v_mfma_f32_16x16x32_bf16 v[38:41], v[204:207], v[226:229], v[38:41]
	v_mfma_f32_16x16x32_bf16 v[6:9], v[174:177], v[242:245], v[6:9]
	v_mfma_f32_16x16x32_bf16 v[2:5], v[204:207], v[242:245], v[2:5]
	s_setprio 0
	s_barrier
	s_add_i32 s27, s27, 2
	s_add_u32 s8, s8, 0x100
	s_addc_u32 s9, s9, 0
	s_add_u32 s5, s5, 0x100
	s_addc_u32 s7, s7, 0
	s_cmp_gt_u32 s27, 13
	s_cbranch_scc0 .LBB0_142
	s_and_b64 vcc, exec, s[18:19]
	s_cbranch_vccz .LBB0_145
	s_barrier

; #define PG8_STAGE(bufoff, gbase, voff) do { _Pragma("unroll") for (int _i = 0; _i < 2; ++_i) \
;         __builtin_amdgcn_global_load_lds((const unsigned*)((const char*)(gbase) + (voff)[_i]), (LAS unsigned*)(lds + (bufoff) + ldsw + _i * 8192), 16, 0, 0); } while (0)
; #define PG8_LDA(dst, b, h) do { _Pragma("unroll") for (int m = 0; m < 4; ++m) _Pragma("unroll") for (int k = 0; k < 2; ++k) dst[m][k] = *(const LAS bf16x8*)(lds + PG8_SA(b, h) + aoff + m * 2048 + k * 1024); } while (0)
; #define PG8_LDB(dst, b, h) do { _Pragma("unroll") for (int n = 0; n < 2; ++n) _Pragma("unroll") for (int k = 0; k < 2; ++k) dst[n][k] = *(const LAS bf16x8*)(lds + PG8_SB(b, h) + boff + n * 2048 + k * 1024); } while (0)
; #define PG8_MMA(ai, bj, At, Bt) do { __builtin_amdgcn_s_setprio(1); _Pragma("unroll") for (int m = 0; m < 4; ++m) _Pragma("unroll") for (int n = 0; n < 2; ++n) _Pragma("unroll") for (int k = 0; k < 2; ++k) \
;         acc[ai][bj][m][n] = __builtin_amdgcn_mfma_f32_16x16x32_bf16(Bt[n][k], At[m][k], acc[ai][bj][m][n], 0, 0, 0); __builtin_amdgcn_s_setprio(0); } while (0)
; #define PG8_WAIT_V(n) asm volatile("s_waitcnt vmcnt(" #n ")" ::: "memory")
; #define PG8_WAIT_L(n) asm volatile("s_waitcnt lgkmcnt(" #n ")" ::: "memory")
; #define PG8_BAR __builtin_amdgcn_s_barrier()
; #define PG8_SCHED __builtin_amdgcn_sched_barrier(0)
; template <class Epi, class Sched>
; __device__ __forceinline__ void gemm_phase(LAS unsigned char* lds, const int K, const Sched& S, const Epi& E) {
;     ...
;             const bool last = (t == nt - 2);
;             const char* a1 = cA + (size_t)(t + 1) * kstep;
;             const char* a2 = last ? nA : cA + (size_t)(t + 2) * kstep; const char* b2 = last ? nB : cB + (size_t)(t + 2) * kstep;
;             const char* a3 = a2 + kstep; const char* b3 = b2 + kstep;
;             PG8_LDB(B0, 0, 0); PG8_LDB(B1, 0, 1); PG8_SCHED; PG8_LDA(At, 0, 0); PG8_STAGE(PG8_SA(1, 1), a1 + hstep, voffA);
;             PG8_WAIT_V(8); PG8_WAIT_L(0); PG8_BAR; PG8_MMA(0, 0, At, B0); PG8_MMA(0, 1, At, B1); PG8_BAR; PG8_SCHED;
;             PG8_LDA(At, 0, 1); PG8_STAGE(PG8_SB(0, 0), b2, voffA); PG8_STAGE(PG8_SB(0, 1), b2 + hstep, voffA); PG8_STAGE(PG8_SA(0, 0), a2, voffA);
;             PG8_WAIT_V(8); PG8_WAIT_L(0); PG8_BAR; PG8_MMA(1, 0, At, B0); PG8_MMA(1, 1, At, B1); PG8_BAR; PG8_SCHED;
.LBB0_819:
	s_add_u32 s34, s30, 0xfffc0080
	s_addc_u32 s35, s31, -1
	s_add_i32 s51, 0, 0x10000
	s_cmp_eq_u32 s50, 12
	s_cselect_b32 s37, s17, s35
	s_cselect_b32 s36, s19, s34
	s_cselect_b32 s35, s27, s39
	s_cselect_b32 s34, s29, s38
	s_add_u32 s60, s36, 0x80
	s_addc_u32 s61, s37, 0
	s_add_u32 s62, s34, 0x80
	s_addc_u32 s63, s35, 0
	s_add_i32 s54, 0, 0x14000
	v_add_u32_e32 v106, s51, v17
	v_add_u32_e32 v170, s54, v17
	ds_read_b128 v[94:97], v106
	ds_read_b128 v[98:101], v106 offset:1024
	ds_read_b128 v[102:105], v106 offset:2048
	ds_read_b128 v[106:109], v106 offset:3072
	ds_read_b128 v[174:177], v170
	ds_read_b128 v[178:181], v170 offset:1024
	ds_read_b128 v[182:185], v170 offset:2048
	ds_read_b128 v[186:189], v170 offset:3072
	s_add_i32 m0, s42, 0xc000
	ds_read_b128 v[190:193], v173
	ds_read_b128 v[194:197], v173 offset:1024
	ds_read_b128 v[198:201], v173 offset:2048
	ds_read_b128 v[202:205], v173 offset:3072
	ds_read_b128 v[206:209], v173 offset:4096
	ds_read_b128 v[210:213], v173 offset:5120
	ds_read_b128 v[214:217], v173 offset:6144
	ds_read_b128 v[218:221], v173 offset:7168
	global_load_lds_dwordx4 v166, s[30:31]
	s_add_i32 m0, s42, 0xe000
	s_nop 0
	global_load_lds_dwordx4 v168, s[30:31]
	s_waitcnt vmcnt(8)
	s_waitcnt lgkmcnt(0)
	s_barrier
	s_setprio 1
	s_waitcnt lgkmcnt(0)
	v_mfma_f32_16x16x32_bf16 v[146:149], v[94:97], v[190:193], v[146:149]
	v_mfma_f32_16x16x32_bf16 v[142:145], v[102:105], v[190:193], v[142:145]
	v_mfma_f32_16x16x32_bf16 v[130:133], v[94:97], v[198:201], v[130:133]
	v_mfma_f32_16x16x32_bf16 v[126:129], v[102:105], v[198:201], v[126:129]
	v_mfma_f32_16x16x32_bf16 v[114:117], v[94:97], v[206:209], v[114:117]
	v_mfma_f32_16x16x32_bf16 v[110:113], v[102:105], v[206:209], v[110:113]
	v_mfma_f32_16x16x32_bf16 v[82:85], v[94:97], v[214:217], v[82:85]
	v_mfma_f32_16x16x32_bf16 v[78:81], v[102:105], v[214:217], v[78:81]
	v_mfma_f32_16x16x32_bf16 v[146:149], v[98:101], v[194:197], v[146:149]
	v_mfma_f32_16x16x32_bf16 v[142:145], v[106:109], v[194:197], v[142:145]
	v_mfma_f32_16x16x32_bf16 v[130:133], v[98:101], v[202:205], v[130:133]
	v_mfma_f32_16x16x32_bf16 v[126:129], v[106:109], v[202:205], v[126:129]
	v_mfma_f32_16x16x32_bf16 v[114:117], v[98:101], v[210:213], v[114:117]
	v_mfma_f32_16x16x32_bf16 v[110:113], v[106:109], v[210:213], v[110:113]
	v_mfma_f32_16x16x32_bf16 v[82:85], v[98:101], v[218:221], v[82:85]
	v_mfma_f32_16x16x32_bf16 v[78:81], v[106:109], v[218:221], v[78:81]
	s_setprio 0
	s_setprio 1
	v_mfma_f32_16x16x32_bf16 v[138:141], v[174:177], v[190:193], v[138:141]
	v_mfma_f32_16x16x32_bf16 v[134:137], v[182:185], v[190:193], v[134:137]
	v_mfma_f32_16x16x32_bf16 v[122:125], v[174:177], v[198:201], v[122:125]
	v_mfma_f32_16x16x32_bf16 v[118:121], v[182:185], v[198:201], v[118:121]
	v_mfma_f32_16x16x32_bf16 v[90:93], v[174:177], v[206:209], v[90:93]
	v_mfma_f32_16x16x32_bf16 v[86:89], v[182:185], v[206:209], v[86:89]
	v_mfma_f32_16x16x32_bf16 v[74:77], v[174:177], v[214:217], v[74:77]
	v_mfma_f32_16x16x32_bf16 v[70:73], v[182:185], v[214:217], v[70:73]
	v_mfma_f32_16x16x32_bf16 v[138:141], v[178:181], v[194:197], v[138:141]
	v_mfma_f32_16x16x32_bf16 v[134:137], v[186:189], v[194:197], v[134:137]
	v_mfma_f32_16x16x32_bf16 v[122:125], v[178:181], v[202:205], v[122:125]
	v_mfma_f32_16x16x32_bf16 v[118:121], v[186:189], v[202:205], v[118:121]
	v_mfma_f32_16x16x32_bf16 v[90:93], v[178:181], v[210:213], v[90:93]
	v_mfma_f32_16x16x32_bf16 v[86:89], v[186:189], v[210:213], v[86:89]
	v_mfma_f32_16x16x32_bf16 v[74:77], v[178:181], v[218:221], v[74:77]
	v_mfma_f32_16x16x32_bf16 v[70:73], v[186:189], v[218:221], v[70:73]
	s_setprio 0
	s_barrier
	s_add_i32 s51, s51, s41
	s_mov_b32 m0, s51
	ds_read_b128 v[190:193], v173 offset:16384
	ds_read_b128 v[194:197], v173 offset:17408
	ds_read_b128 v[198:201], v173 offset:18432
	ds_read_b128 v[202:205], v173 offset:19456
	ds_read_b128 v[206:209], v173 offset:20480
	ds_read_b128 v[210:213], v173 offset:21504
	ds_read_b128 v[214:217], v173 offset:22528
	ds_read_b128 v[218:221], v173 offset:23552
	global_load_lds_dwordx4 v0, s[34:35]
	s_add_i32 m0, s51, 0x2000
	s_add_u32 s52, s34, 0x40000
	s_addc_u32 s53, s35, 0
	s_add_i32 s51, s54, s41
	global_load_lds_dwordx4 v14, s[34:35]
	s_mov_b32 m0, s51
	s_nop 0
	global_load_lds_dwordx4 v0, s[52:53]
	s_add_i32 m0, s51, 0x2000
	s_nop 0
	global_load_lds_dwordx4 v14, s[52:53]
	s_mov_b32 m0, s42
	s_nop 0
	global_load_lds_dwordx4 v0, s[36:37]
	s_mov_b32 m0, s43
	s_nop 0
	global_load_lds_dwordx4 v14, s[36:37]
	s_waitcnt vmcnt(8)
	s_waitcnt lgkmcnt(0)
	s_barrier
; #define PG8_STAGE(bufoff, gbase, voff) do { _Pragma("unroll") for (int _i = 0; _i < 2; ++_i) \
;         __builtin_amdgcn_global_load_lds((const unsigned*)((const char*)(gbase) + (voff)[_i]), (LAS unsigned*)(lds + (bufoff) + ldsw + _i * 8192), 16, 0, 0); } while (0)
; #define PG8_LDA(dst, b, h) do { _Pragma("unroll") for (int m = 0; m < 4; ++m) _Pragma("unroll") for (int k = 0; k < 2; ++k) dst[m][k] = *(const LAS bf16x8*)(lds + PG8_SA(b, h) + aoff + m * 2048 + k * 1024); } while (0)
; #define PG8_LDB(dst, b, h) do { _Pragma("unroll") for (int n = 0; n < 2; ++n) _Pragma("unroll") for (int k = 0; k < 2; ++k) dst[n][k] = *(const LAS bf16x8*)(lds + PG8_SB(b, h) + boff + n * 2048 + k * 1024); } while (0)
; #define PG8_MMA(ai, bj, At, Bt) do { __builtin_amdgcn_s_setprio(1); _Pragma("unroll") for (int m = 0; m < 4; ++m) _Pragma("unroll") for (int n = 0; n < 2; ++n) _Pragma("unroll") for (int k = 0; k < 2; ++k) \
;         acc[ai][bj][m][n] = __builtin_amdgcn_mfma_f32_16x16x32_bf16(Bt[n][k], At[m][k], acc[ai][bj][m][n], 0, 0, 0); __builtin_amdgcn_s_setprio(0); } while (0)
; #define PG8_WAIT_V(n) asm volatile("s_waitcnt vmcnt(" #n ")" ::: "memory")
; #define PG8_WAIT_L(n) asm volatile("s_waitcnt lgkmcnt(" #n ")" ::: "memory")
; #define PG8_BAR __builtin_amdgcn_s_barrier()
; #define PG8_SCHED __builtin_amdgcn_sched_barrier(0)
; template <class Epi, class Sched>
; __device__ __forceinline__ void gemm_phase(LAS unsigned char* lds, const int K, const Sched& S, const Epi& E) {
;     ...
;             PG8_WAIT_V(8); PG8_WAIT_L(0); PG8_BAR; PG8_MMA(1, 0, At, B0); PG8_MMA(1, 1, At, B1); PG8_BAR; PG8_SCHED;
;             PG8_LDB(B0, 1, 0); PG8_LDB(B1, 1, 1); PG8_SCHED; PG8_LDA(At, 1, 0); PG8_STAGE(PG8_SA(0, 1), a2 + hstep, voffA);
;             PG8_WAIT_V(8); PG8_WAIT_L(0); PG8_BAR; PG8_MMA(0, 0, At, B0); PG8_MMA(0, 1, At, B1); PG8_BAR; PG8_SCHED;
	s_setprio 1
	s_waitcnt lgkmcnt(0)
	v_mfma_f32_16x16x32_bf16 v[66:69], v[94:97], v[190:193], v[66:69]
	v_mfma_f32_16x16x32_bf16 v[62:65], v[102:105], v[190:193], v[62:65]
	v_mfma_f32_16x16x32_bf16 v[50:53], v[94:97], v[198:201], v[50:53]
	v_mfma_f32_16x16x32_bf16 v[46:49], v[102:105], v[198:201], v[46:49]
	v_mfma_f32_16x16x32_bf16 v[34:37], v[94:97], v[206:209], v[34:37]
	v_mfma_f32_16x16x32_bf16 v[30:33], v[102:105], v[206:209], v[30:33]
	v_mfma_f32_16x16x32_bf16 v[18:21], v[94:97], v[214:217], v[18:21]
	v_mfma_f32_16x16x32_bf16 v[10:13], v[102:105], v[214:217], v[10:13]
	v_mfma_f32_16x16x32_bf16 v[66:69], v[98:101], v[194:197], v[66:69]
	v_mfma_f32_16x16x32_bf16 v[62:65], v[106:109], v[194:197], v[62:65]
	v_mfma_f32_16x16x32_bf16 v[50:53], v[98:101], v[202:205], v[50:53]
	v_mfma_f32_16x16x32_bf16 v[46:49], v[106:109], v[202:205], v[46:49]
	v_mfma_f32_16x16x32_bf16 v[34:37], v[98:101], v[210:213], v[34:37]
	v_mfma_f32_16x16x32_bf16 v[30:33], v[106:109], v[210:213], v[30:33]
	v_mfma_f32_16x16x32_bf16 v[18:21], v[98:101], v[218:221], v[18:21]
	v_mfma_f32_16x16x32_bf16 v[10:13], v[106:109], v[218:221], v[10:13]
	s_setprio 0
	s_setprio 1
	v_mfma_f32_16x16x32_bf16 v[58:61], v[174:177], v[190:193], v[58:61]
	v_mfma_f32_16x16x32_bf16 v[54:57], v[182:185], v[190:193], v[54:57]
	v_mfma_f32_16x16x32_bf16 v[42:45], v[174:177], v[198:201], v[42:45]
	v_mfma_f32_16x16x32_bf16 v[38:41], v[182:185], v[198:201], v[38:41]
	v_mfma_f32_16x16x32_bf16 v[26:29], v[174:177], v[206:209], v[26:29]
	v_mfma_f32_16x16x32_bf16 v[22:25], v[182:185], v[206:209], v[22:25]
	v_mfma_f32_16x16x32_bf16 v[6:9], v[174:177], v[214:217], v[6:9]
	v_mfma_f32_16x16x32_bf16 v[2:5], v[182:185], v[214:217], v[2:5]
	v_mfma_f32_16x16x32_bf16 v[58:61], v[178:181], v[194:197], v[58:61]
	v_mfma_f32_16x16x32_bf16 v[54:57], v[186:189], v[194:197], v[54:57]
	v_mfma_f32_16x16x32_bf16 v[42:45], v[178:181], v[202:205], v[42:45]
	v_mfma_f32_16x16x32_bf16 v[38:41], v[186:189], v[202:205], v[38:41]
	v_mfma_f32_16x16x32_bf16 v[26:29], v[178:181], v[210:213], v[26:29]
	v_mfma_f32_16x16x32_bf16 v[22:25], v[186:189], v[210:213], v[22:25]
	v_mfma_f32_16x16x32_bf16 v[6:9], v[178:181], v[218:221], v[6:9]
	v_mfma_f32_16x16x32_bf16 v[2:5], v[186:189], v[218:221], v[2:5]
	s_setprio 0
	s_barrier
	s_add_i32 s51, 0, 0x18000
	s_add_i32 s52, 0, 0x1c000
	v_add_u32_e32 v106, s51, v17
	v_add_u32_e32 v186, s52, v17
	ds_read_b128 v[94:97], v106
	ds_read_b128 v[98:101], v106 offset:1024
	ds_read_b128 v[102:105], v106 offset:2048
	ds_read_b128 v[106:109], v106 offset:3072
	ds_read_b128 v[174:177], v186
	ds_read_b128 v[178:181], v186 offset:1024
	ds_read_b128 v[182:185], v186 offset:2048
	ds_read_b128 v[186:189], v186 offset:3072
	s_add_u32 s36, s36, 0x40000
	s_addc_u32 s37, s37, 0
	s_mov_b32 m0, s45
	ds_read_b128 v[190:193], v173 offset:32768
	ds_read_b128 v[194:197], v173 offset:33792
	ds_read_b128 v[198:201], v173 offset:34816
	ds_read_b128 v[202:205], v173 offset:35840
	ds_read_b128 v[206:209], v173 offset:36864
	ds_read_b128 v[210:213], v173 offset:37888
	ds_read_b128 v[214:217], v173 offset:38912
	ds_read_b128 v[218:221], v173 offset:39936
	global_load_lds_dwordx4 v0, s[36:37]
	s_mov_b32 m0, s46
	s_nop 0
	global_load_lds_dwordx4 v14, s[36:37]
	s_waitcnt vmcnt(8)
	s_waitcnt lgkmcnt(0)
	s_barrier
	s_setprio 1
	s_waitcnt lgkmcnt(0)
	v_mfma_f32_16x16x32_bf16 v[146:149], v[94:97], v[190:193], v[146:149]
	v_mfma_f32_16x16x32_bf16 v[142:145], v[102:105], v[190:193], v[142:145]
	v_mfma_f32_16x16x32_bf16 v[130:133], v[94:97], v[198:201], v[130:133]
	v_mfma_f32_16x16x32_bf16 v[126:129], v[102:105], v[198:201], v[126:129]
	v_mfma_f32_16x16x32_bf16 v[114:117], v[94:97], v[206:209], v[114:117]
	v_mfma_f32_16x16x32_bf16 v[110:113], v[102:105], v[206:209], v[110:113]
	v_mfma_f32_16x16x32_bf16 v[82:85], v[94:97], v[214:217], v[82:85]
	v_mfma_f32_16x16x32_bf16 v[78:81], v[102:105], v[214:217], v[78:81]
	v_mfma_f32_16x16x32_bf16 v[146:149], v[98:101], v[194:197], v[146:149]
	v_mfma_f32_16x16x32_bf16 v[142:145], v[106:109], v[194:197], v[142:145]
	v_mfma_f32_16x16x32_bf16 v[130:133], v[98:101], v[202:205], v[130:133]
	v_mfma_f32_16x16x32_bf16 v[126:129], v[106:109], v[202:205], v[126:129]
	v_mfma_f32_16x16x32_bf16 v[114:117], v[98:101], v[210:213], v[114:117]
	v_mfma_f32_16x16x32_bf16 v[110:113], v[106:109], v[210:213], v[110:113]
	v_mfma_f32_16x16x32_bf16 v[82:85], v[98:101], v[218:221], v[82:85]
	v_mfma_f32_16x16x32_bf16 v[78:81], v[106:109], v[218:221], v[78:81]
	s_setprio 0
	s_setprio 1
	v_mfma_f32_16x16x32_bf16 v[138:141], v[174:177], v[190:193], v[138:141]
	v_mfma_f32_16x16x32_bf16 v[134:137], v[182:185], v[190:193], v[134:137]
	v_mfma_f32_16x16x32_bf16 v[122:125], v[174:177], v[198:201], v[122:125]
	v_mfma_f32_16x16x32_bf16 v[118:121], v[182:185], v[198:201], v[118:121]
	v_mfma_f32_16x16x32_bf16 v[90:93], v[174:177], v[206:209], v[90:93]
	v_mfma_f32_16x16x32_bf16 v[86:89], v[182:185], v[206:209], v[86:89]
	v_mfma_f32_16x16x32_bf16 v[74:77], v[174:177], v[214:217], v[74:77]
	v_mfma_f32_16x16x32_bf16 v[70:73], v[182:185], v[214:217], v[70:73]
	v_mfma_f32_16x16x32_bf16 v[138:141], v[178:181], v[194:197], v[138:141]
	v_mfma_f32_16x16x32_bf16 v[134:137], v[186:189], v[194:197], v[134:137]
	v_mfma_f32_16x16x32_bf16 v[122:125], v[178:181], v[202:205], v[122:125]
	v_mfma_f32_16x16x32_bf16 v[118:121], v[186:189], v[202:205], v[118:121]
	v_mfma_f32_16x16x32_bf16 v[90:93], v[178:181], v[210:213], v[90:93]
	v_mfma_f32_16x16x32_bf16 v[86:89], v[186:189], v[210:213], v[86:89]
	v_mfma_f32_16x16x32_bf16 v[74:77], v[178:181], v[218:221], v[74:77]
	v_mfma_f32_16x16x32_bf16 v[70:73], v[186:189], v[218:221], v[70:73]
	s_setprio 0
	s_barrier
; #define PG8_STAGE(bufoff, gbase, voff) do { _Pragma("unroll") for (int _i = 0; _i < 2; ++_i) \
;         __builtin_amdgcn_global_load_lds((const unsigned*)((const char*)(gbase) + (voff)[_i]), (LAS unsigned*)(lds + (bufoff) + ldsw + _i * 8192), 16, 0, 0); } while (0)
; #define PG8_LDA(dst, b, h) do { _Pragma("unroll") for (int m = 0; m < 4; ++m) _Pragma("unroll") for (int k = 0; k < 2; ++k) dst[m][k] = *(const LAS bf16x8*)(lds + PG8_SA(b, h) + aoff + m * 2048 + k * 1024); } while (0)
; #define PG8_MMA(ai, bj, At, Bt) do { __builtin_amdgcn_s_setprio(1); _Pragma("unroll") for (int m = 0; m < 4; ++m) _Pragma("unroll") for (int n = 0; n < 2; ++n) _Pragma("unroll") for (int k = 0; k < 2; ++k) \
;         acc[ai][bj][m][n] = __builtin_amdgcn_mfma_f32_16x16x32_bf16(Bt[n][k], At[m][k], acc[ai][bj][m][n], 0, 0, 0); __builtin_amdgcn_s_setprio(0); } while (0)
; #define PG8_WAIT_V(n) asm volatile("s_waitcnt vmcnt(" #n ")" ::: "memory")
; #define PG8_WAIT_L(n) asm volatile("s_waitcnt lgkmcnt(" #n ")" ::: "memory")
; #define PG8_BAR __builtin_amdgcn_s_barrier()
; #define PG8_SCHED __builtin_amdgcn_sched_barrier(0)
; template <class Epi, class Sched>
; __device__ __forceinline__ void gemm_phase(LAS unsigned char* lds, const int K, const Sched& S, const Epi& E) {
;     ...
;             PG8_LDA(At, 1, 1); PG8_STAGE(PG8_SB(1, 0), b3, voffA); PG8_STAGE(PG8_SB(1, 1), b3 + hstep, voffA); PG8_STAGE(PG8_SA(1, 0), a3, voffA);
;             PG8_WAIT_V(8); PG8_WAIT_L(0); PG8_BAR; PG8_MMA(1, 0, At, B0); PG8_MMA(1, 1, At, B1); PG8_BAR; PG8_SCHED;
;         }
	s_add_i32 s36, s51, s41
	s_mov_b32 m0, s36
	ds_read_b128 v[190:193], v173 offset:49152
	ds_read_b128 v[194:197], v173 offset:50176
	ds_read_b128 v[198:201], v173 offset:51200
	ds_read_b128 v[202:205], v173 offset:52224
	ds_read_b128 v[206:209], v173 offset:53248
	ds_read_b128 v[210:213], v173 offset:54272
	ds_read_b128 v[214:217], v173 offset:55296
	ds_read_b128 v[218:221], v173 offset:56320
	global_load_lds_dwordx4 v0, s[62:63]
	s_add_i32 m0, s36, 0x2000
	s_add_u32 s34, s34, 0x40080
	s_addc_u32 s35, s35, 0
	s_add_i32 s36, s52, s41
	global_load_lds_dwordx4 v14, s[62:63]
	s_mov_b32 m0, s36
	s_nop 0
	global_load_lds_dwordx4 v0, s[34:35]
	s_add_i32 m0, s36, 0x2000
	s_nop 0
	global_load_lds_dwordx4 v14, s[34:35]
	s_mov_b32 m0, s47
	s_nop 0
	global_load_lds_dwordx4 v0, s[60:61]
	s_mov_b32 m0, s48
	s_nop 0
	global_load_lds_dwordx4 v14, s[60:61]
	s_waitcnt vmcnt(8)
	s_waitcnt lgkmcnt(0)
	s_barrier
	s_setprio 1
	s_waitcnt lgkmcnt(0)
	v_mfma_f32_16x16x32_bf16 v[66:69], v[94:97], v[190:193], v[66:69]
	v_mfma_f32_16x16x32_bf16 v[62:65], v[102:105], v[190:193], v[62:65]
	v_mfma_f32_16x16x32_bf16 v[50:53], v[94:97], v[198:201], v[50:53]
	v_mfma_f32_16x16x32_bf16 v[46:49], v[102:105], v[198:201], v[46:49]
	v_mfma_f32_16x16x32_bf16 v[34:37], v[94:97], v[206:209], v[34:37]
	v_mfma_f32_16x16x32_bf16 v[30:33], v[102:105], v[206:209], v[30:33]
	v_mfma_f32_16x16x32_bf16 v[18:21], v[94:97], v[214:217], v[18:21]
	v_mfma_f32_16x16x32_bf16 v[10:13], v[102:105], v[214:217], v[10:13]
	v_mfma_f32_16x16x32_bf16 v[66:69], v[98:101], v[194:197], v[66:69]
	v_mfma_f32_16x16x32_bf16 v[62:65], v[106:109], v[194:197], v[62:65]
	v_mfma_f32_16x16x32_bf16 v[50:53], v[98:101], v[202:205], v[50:53]
	v_mfma_f32_16x16x32_bf16 v[46:49], v[106:109], v[202:205], v[46:49]
	v_mfma_f32_16x16x32_bf16 v[34:37], v[98:101], v[210:213], v[34:37]
	v_mfma_f32_16x16x32_bf16 v[30:33], v[106:109], v[210:213], v[30:33]
	v_mfma_f32_16x16x32_bf16 v[18:21], v[98:101], v[218:221], v[18:21]
	v_mfma_f32_16x16x32_bf16 v[10:13], v[106:109], v[218:221], v[10:13]
	s_setprio 0
	s_setprio 1
	v_mfma_f32_16x16x32_bf16 v[58:61], v[174:177], v[190:193], v[58:61]
	v_mfma_f32_16x16x32_bf16 v[54:57], v[182:185], v[190:193], v[54:57]
	v_mfma_f32_16x16x32_bf16 v[42:45], v[174:177], v[198:201], v[42:45]
	v_mfma_f32_16x16x32_bf16 v[38:41], v[182:185], v[198:201], v[38:41]
	v_mfma_f32_16x16x32_bf16 v[26:29], v[174:177], v[206:209], v[26:29]
	v_mfma_f32_16x16x32_bf16 v[22:25], v[182:185], v[206:209], v[22:25]
	v_mfma_f32_16x16x32_bf16 v[6:9], v[174:177], v[214:217], v[6:9]
	v_mfma_f32_16x16x32_bf16 v[2:5], v[182:185], v[214:217], v[2:5]
	v_mfma_f32_16x16x32_bf16 v[58:61], v[178:181], v[194:197], v[58:61]
	v_mfma_f32_16x16x32_bf16 v[54:57], v[186:189], v[194:197], v[54:57]
	v_mfma_f32_16x16x32_bf16 v[42:45], v[178:181], v[202:205], v[42:45]
	v_mfma_f32_16x16x32_bf16 v[38:41], v[186:189], v[202:205], v[38:41]
	v_mfma_f32_16x16x32_bf16 v[26:29], v[178:181], v[210:213], v[26:29]
	v_mfma_f32_16x16x32_bf16 v[22:25], v[186:189], v[210:213], v[22:25]
	v_mfma_f32_16x16x32_bf16 v[6:9], v[178:181], v[218:221], v[6:9]
	v_mfma_f32_16x16x32_bf16 v[2:5], v[186:189], v[218:221], v[2:5]
	s_setprio 0
	s_barrier
	s_add_i32 s50, s50, 2
	s_add_u32 s30, s30, 0x100
	s_addc_u32 s31, s31, 0
	s_add_u32 s38, s38, 0x100
	s_addc_u32 s39, s39, 0
	s_cmp_gt_u32 s50, 13
	s_cbranch_scc0 .LBB0_819
	s_and_b64 vcc, exec, s[14:15]
	s_cbranch_vccz .LBB0_822
	s_barrier
